# attn7: 3-slot LDS ring, 2-deep global prefetch, staging mid-iteration, next-tile K fragments prefetched across the barrier (+v029 changes)
# baseline (speedup 1.0000x reference)
; #define A_LOAD(t) do { kreg0 = *(const u32x4*)(kg + (size_t)((t) * 64 + kv0) * 768 + kc0 * 8); if (tid < 256) kreg1 = *(const u32x4*)(kg + (size_t)((t) * 64 + kv1) * 768 + kc1 * 8); \
;         vreg = *(const u32x4*)(vg + (size_t)(t) * 64 * 512); } while (0)
; __device__ __forceinline__ void attn_unit(LAS unsigned char* lds, const bf16* Q, const bf16* Kp, const bf16* V, bf16* Y, int b, int h, int qb) {
;     ...
;     const int kv0 = tid / 12, kc0 = tid % 12, kv1 = (tid + 512) / 12, kc1 = (tid + 512) % 12;
;     const bf16* kg = Kp + rowbase * 768 + h * 96;
;     const bf16* vg = V + (rowbase + (tid & 63)) * 512 + h * 64 + 8 * (tid >> 6);
;     u32x4 kreg0, kreg1 = (u32x4){0, 0, 0, 0}, vreg;
;     ...
;     A_LOAD(0); A_STORE(0);
;     __syncthreads();
;     float m_run = 0.f, l_run = 0.f;
;     f32x16 o[2];
; #pragma unroll
;     for (int i = 0; i < 16; ++i) { o[0][i] = 0.f; o[1][i] = 0.f; }
;     const int qrel = wid * 32 + r32;
.LBB0_3632:
	s_or_b64 exec, exec, s[10:11]
	v_and_b32_e32 v11, 63, v4
	v_or_b32_e32 v4, s13, v11
	v_lshlrev_b32_e32 v4, 10, v4
	v_mov_b32_e32 v5, v64
	v_lshl_add_u64 v[4:5], s[64:65], 0, v[4:5]
	s_lshl_b32 s80, s9, 7
	v_lshl_add_u64 v[14:15], v[4:5], 0, s[80:81]
	v_lshlrev_b32_e32 v4, 3, v8
	v_ashrrev_i32_e32 v5, 31, v4
	v_lshl_add_u64 v[14:15], v[4:5], 1, v[14:15]
	flat_load_dwordx4 v[100:103], v[14:15]
	s_movk_i32 s10, 0xd0
	v_mul_lo_u32 v65, v9, s10
	v_lshlrev_b32_e32 v111, 4, v12
	v_add3_u32 v12, 0, v65, v111
	v_lshlrev_b32_e32 v113, 4, v13
	s_waitcnt vmcnt(0) lgkmcnt(0)
	ds_write_b128 v12, v[92:95]
	s_and_saveexec_b64 s[10:11], vcc
	s_xor_b64 s[10:11], exec, s[10:11]
	v_lshlrev_b32_e32 v113, 4, v13
	s_or_saveexec_b64 s[10:11], s[10:11]
	s_movk_i32 s13, 0xd0
	v_mul_lo_u32 v114, v10, s13
	s_xor_b64 exec, exec, s[10:11]
	v_add3_u32 v12, 0, v114, v113
	ds_write_b128 v12, v[96:99]
	s_or_b64 exec, exec, s[10:11]
	v_lshl_add_u64 v[66:67], v[0:1], 1, s[6:7]
	v_lshl_add_u64 v[106:107], v[2:3], 1, s[6:7]
	s_movk_i32 s6, 0xd0
	v_lshlrev_b32_e32 v12, 3, v6
	v_mad_u32_u24 v0, v7, s6, 0
	v_mul_i32_i24_e32 v1, 0xffffffb8, v7
	v_lshl_add_u32 v117, v6, 4, v0
	v_add3_u32 v118, v0, v1, v12
	v_mov_b32_e32 v0, s80
	v_mov_b32_e32 v1, v64
	v_lshlrev_b32_e32 v2, 10, v11
	s_movk_i32 s10, 0x440
	v_lshl_add_u64 v[0:1], v[4:5], 1, v[0:1]
	v_lshl_or_b32 v2, s23, 23, v2
	v_mov_b32_e32 v3, v64
	s_lshl_b32 s12, s12, 2
	v_mul_lo_u32 v8, v8, s10
	v_lshlrev_b32_e32 v13, 1, v11
	v_lshlrev_b32_e32 v112, 2, v6
	s_lshl_b32 s15, s22, 8
	v_lshl_add_u64 v[0:1], v[0:1], 0, v[2:3]
	v_mov_b32_e32 v123, 0
	s_lshl_b32 s9, s9, 6
	s_add_i32 s12, s12, 4
	s_mov_b32 s13, 1
	v_add3_u32 v115, 0, v8, v13
	v_or_b32_e32 v116, s14, v7
	s_or_b32 s14, s14, 31
	v_or_b32_e32 v119, s15, v112
	s_lshl_b32 s22, s22, 2
	v_add_u32_e32 v120, 64, v10
	v_add_u32_e32 v121, 64, v9
	v_lshl_add_u64 v[108:109], s[4:5], 0, v[0:1]
	s_mov_b32 s23, 0
	v_mov_b32_e32 v122, 0
	v_mov_b32_e32 v16, 0
	v_mov_b32_e32 v17, v123
	v_mov_b32_e32 v18, v123
	v_mov_b32_e32 v19, v123
	v_mov_b32_e32 v20, v123
	v_mov_b32_e32 v21, v123
	v_mov_b32_e32 v22, v123
	v_mov_b32_e32 v23, v123
	v_mov_b32_e32 v24, v123
	v_mov_b32_e32 v25, v123
	v_mov_b32_e32 v26, v123
	v_mov_b32_e32 v27, v123
	v_mov_b32_e32 v28, v123
	v_mov_b32_e32 v29, v123
	v_mov_b32_e32 v30, v123
	v_mov_b32_e32 v31, v123
	v_mov_b32_e32 v0, v123
	v_mov_b32_e32 v1, v123
	v_mov_b32_e32 v2, v123
	v_mov_b32_e32 v3, v123
	v_mov_b32_e32 v4, v123
	v_mov_b32_e32 v5, v123
	v_mov_b32_e32 v6, v123
	v_mov_b32_e32 v7, v123
	v_mov_b32_e32 v8, v123
	v_mov_b32_e32 v9, v123
	v_mov_b32_e32 v10, v123
	v_mov_b32_e32 v11, v123
	v_mov_b32_e32 v12, v123
	v_mov_b32_e32 v13, v123
	v_mov_b32_e32 v14, v123
	v_mov_b32_e32 v15, v123
	ds_write_b16 v115, v100 offset:26624
	ds_write_b16_d16_hi v115, v100 offset:26760
	ds_write_b16 v115, v101 offset:26896
	ds_write_b16_d16_hi v115, v101 offset:27032
	ds_write_b16 v115, v102 offset:27168
	ds_write_b16_d16_hi v115, v102 offset:27304
	ds_write_b16 v115, v103 offset:27440
	ds_write_b16_d16_hi v115, v103 offset:27576
	v_add_u32_e32 v32, s23, v121
	v_mad_i64_i32 v[32:33], s[10:11], v32, s87, v[66:67]
	global_load_dwordx4 v[142:145], v[32:33], off
	v_mov_b64_e32 v[34:35], v[32:33]
	s_and_saveexec_b64 s[10:11], s[38:39]
	v_add_u32_e32 v36, s23, v120
	v_mad_i64_i32 v[34:35], s[24:25], v36, s87, v[106:107]
	s_or_b64 exec, exec, s[10:11]
	global_load_dwordx4 v[146:149], v[34:35], off
	global_load_dwordx4 v[150:153], v[108:109], off
	s_mov_b64 s[6:7], 0x10000
	v_lshl_add_u64 v[108:109], v[108:109], 0, s[6:7]
	s_movk_i32 s46, 0x3400
	s_movk_i32 s47, 0x2200
	s_waitcnt vmcnt(0)
	v_add3_u32 v110, s46, v65, v111
	ds_write_b128 v110, v[142:145]
	s_and_saveexec_b64 s[54:55], s[38:39]
	s_cbranch_execz .Lat_st2pre
	v_add3_u32 v110, s46, v114, v113
	ds_write_b128 v110, v[146:149]
; #define LAS __attribute__((address_space(3)))
; #define A_LOAD(t) do { kreg0 = *(const u32x4*)(kg + (size_t)((t) * 64 + kv0) * 768 + kc0 * 8); if (tid < 256) kreg1 = *(const u32x4*)(kg + (size_t)((t) * 64 + kv1) * 768 + kc1 * 8); \
;         vreg = *(const u32x4*)(vg + (size_t)(t) * 64 * 512); } while (0)
; __device__ __forceinline__ void attn_unit(LAS unsigned char* lds, const bf16* Q, const bf16* Kp, const bf16* V, bf16* Y, int b, int h, int qb) {
;     ...
;     for (int t = 0; t < NT; ++t) {
;         const int buf = t & 1;
;         if (t + 1 < NT) A_LOAD(t + 1);
;         const int jb = t - (NT - 4);
;         const bool skip = (jb >= 0) && (64 * jb > wid * 32 + 31);
;         if (!skip) {
;             f32x16 p0, p1;
;             const float nm = -m_run;
; #pragma unroll
;             for (int i = 0; i < 16; ++i) { p0[i] = nm; p1[i] = nm; }
;             LAS const unsigned char* kb = lds + KOFF + buf * KBUF + r32 * KPB + hi * 16;
;             LAS const unsigned char* vb = lds + VOFF + buf * VBUF + r32 * VPB + hi * 8;
; #pragma unroll
;             for (int d0 = 0; d0 < 6; ++d0) p0 = __builtin_amdgcn_mfma_f32_32x32x16_bf16(*(LAS const bf16x8*)(kb + 32 * d0), qr[d0], p0, 0, 0, 0);
; #pragma unroll
;             for (int d0 = 0; d0 < 6; ++d0) p1 = __builtin_amdgcn_mfma_f32_32x32x16_bf16(*(LAS const bf16x8*)(kb + 32 * KPB + 32 * d0), qr[d0], p1, 0, 0, 0);
.Lat_st2pre:
	s_or_b64 exec, exec, s[54:55]
	v_add_u32_e32 v110, s47, v115
	ds_write_b16 v110, v150 offset:26624
	ds_write_b16_d16_hi v110, v150 offset:26760
	ds_write_b16 v110, v151 offset:26896
	ds_write_b16_d16_hi v110, v151 offset:27032
	ds_write_b16 v110, v152 offset:27168
	ds_write_b16_d16_hi v110, v152 offset:27304
	ds_write_b16 v110, v153 offset:27440
	ds_write_b16_d16_hi v110, v153 offset:27576
	s_waitcnt lgkmcnt(0)
	v_add_u32_e32 v32, s23, v121
	v_add_u32_e32 v32, 0x40, v32
	v_mad_i64_i32 v[32:33], s[10:11], v32, s87, v[66:67]
	global_load_dwordx4 v[142:145], v[32:33], off
	v_mov_b64_e32 v[34:35], v[32:33]
	s_and_saveexec_b64 s[10:11], s[38:39]
	v_add_u32_e32 v36, s23, v120
	v_add_u32_e32 v36, 0x40, v36
	v_mad_i64_i32 v[34:35], s[24:25], v36, s87, v[106:107]
	s_or_b64 exec, exec, s[10:11]
	global_load_dwordx4 v[146:149], v[34:35], off
	global_load_dwordx4 v[150:153], v[108:109], off
	s_mov_b64 s[6:7], 0x10000
	v_lshl_add_u64 v[108:109], v[108:109], 0, s[6:7]
	s_mov_b32 s44, 0
	s_mov_b32 s45, 0
	s_mov_b32 s48, 0xce00
	s_movk_i32 s49, 0x4400
	s_mov_b64 s[66:67], -1
	s_waitcnt lgkmcnt(0)
	s_barrier
	v_add_u32_e32 v110, s44, v117
	ds_read_b128 v[172:175], v110
	ds_read_b128 v[176:179], v110 offset:32
	ds_read_b128 v[180:183], v110 offset:64
	ds_read_b128 v[184:187], v110 offset:96
	ds_read_b128 v[188:191], v110 offset:128
	ds_read_b128 v[192:195], v110 offset:160
	ds_read_b128 v[198:201], v110 offset:6656
	ds_read_b128 v[202:205], v110 offset:6688
	ds_read_b128 v[206:209], v110 offset:6720
	ds_read_b128 v[222:225], v110 offset:6752
	ds_read_b128 v[226:229], v110 offset:6784
	ds_read_b128 v[230:233], v110 offset:6816
	s_branch .Lat_head
.Lat_head:
	s_add_i32 s25, s13, 2
	s_cmp_lt_u32 s25, s12
	s_cselect_b64 s[50:51], -1, 0
	s_cbranch_scc0 .Lat_noload_0
	v_add_u32_e32 v32, s23, v121
	v_add_u32_e32 v32, 0x80, v32
	v_mad_i64_i32 v[32:33], s[10:11], v32, s87, v[66:67]
	global_load_dwordx4 v[92:95], v[32:33], off
	v_mov_b64_e32 v[34:35], v[32:33]
	s_and_saveexec_b64 s[10:11], s[38:39]
	v_add_u32_e32 v36, s23, v120
	v_add_u32_e32 v36, 0x80, v36
	v_mad_i64_i32 v[34:35], s[24:25], v36, s87, v[106:107]
	s_or_b64 exec, exec, s[10:11]
	global_load_dwordx4 v[96:99], v[34:35], off
	global_load_dwordx4 v[100:103], v[108:109], off
.Lat_noload_0:
	s_add_i32 s25, s13, 1
	s_cmp_lt_u32 s25, s12
	s_cselect_b64 s[6:7], -1, 0
	s_cmp_lt_u32 s13, s12
	s_cselect_b64 s[52:53], -1, 0
	s_add_i32 s10, s22, s13
	s_addk_i32 s10, 0xff83
	s_cmp_gt_i32 s10, -1
	s_cselect_b64 s[10:11], -1, 0
	s_add_i32 s25, s15, s23
	s_addk_i32 s25, 0xe100
	s_cmp_gt_i32 s25, s14
	s_cselect_b64 s[26:27], -1, 0
	s_and_b64 s[26:27], s[10:11], s[26:27]
	s_and_b64 vcc, exec, s[26:27]
	s_cbranch_vccnz .Lat_stage_0
	v_add_u32_e32 v124, s45, v118
	v_add_u32_e32 v124, 0x6800, v124
	v_add_u32_e32 v125, 0x1000, v124
	v_xor_b32_e32 v48, 0x80000000, v122
	v_mov_b32_e32 v49, v48
	v_mov_b32_e32 v50, v48
	v_mov_b32_e32 v51, v48
	v_mov_b32_e32 v52, v48
	v_mov_b32_e32 v53, v48
	v_mov_b32_e32 v54, v48
	v_mov_b32_e32 v55, v48
	v_mov_b32_e32 v56, v48
	v_mov_b32_e32 v57, v48
	v_mov_b32_e32 v58, v48
	v_mov_b32_e32 v59, v48
	v_mov_b32_e32 v60, v48
	v_mov_b32_e32 v61, v48
	v_mov_b32_e32 v62, v48
	v_mov_b32_e32 v63, v48
	s_waitcnt lgkmcnt(0)
	s_nop 0
	v_mfma_f32_32x32x16_bf16 v[32:47], v[172:175], v[68:71], v[48:63]
	ds_read2_b64 v[234:237], v124 offset1:2
	v_mfma_f32_32x32x16_bf16 v[32:47], v[176:179], v[72:75], v[32:47]
	ds_read2_b64 v[238:241], v124 offset0:4 offset1:6
	v_mfma_f32_32x32x16_bf16 v[32:47], v[180:183], v[76:79], v[32:47]
	ds_read2_b64 v[242:245], v125 offset0:32 offset1:34
	v_mfma_f32_32x32x16_bf16 v[32:47], v[184:187], v[80:83], v[32:47]
	ds_read2_b64 v[246:249], v125 offset0:36 offset1:38
	v_mfma_f32_32x32x16_bf16 v[32:47], v[188:191], v[84:87], v[32:47]
	v_mfma_f32_32x32x16_bf16 v[32:47], v[192:195], v[88:91], v[32:47]
	v_mfma_f32_32x32x16_bf16 v[48:63], v[198:201], v[68:71], v[48:63]
	v_mfma_f32_32x32x16_bf16 v[48:63], v[202:205], v[72:75], v[48:63]
	v_mfma_f32_32x32x16_bf16 v[48:63], v[206:209], v[76:79], v[48:63]
	s_andn2_b64 vcc, exec, s[6:7]
	s_cbranch_vccnz .Lat_nost_0
	s_waitcnt lgkmcnt(0)
	s_and_b64 vcc, exec, s[50:51]
	s_cbranch_vccz .Lat_w0h_0
	s_waitcnt vmcnt(3)
	s_branch .Lat_w1h_0

.Lat_w1h_0:
	v_add3_u32 v110, s48, v65, v111
	ds_write_b128 v110, v[142:145]
	s_and_saveexec_b64 s[54:55], s[38:39]
	s_cbranch_execz .Lat_st2h_0
	v_add3_u32 v110, s48, v114, v113
	ds_write_b128 v110, v[146:149]
.Lat_st2h_0:
	s_or_b64 exec, exec, s[54:55]
	v_add_u32_e32 v110, s49, v115
	ds_write_b16 v110, v150 offset:26624
	ds_write_b16_d16_hi v110, v150 offset:26760
	ds_write_b16 v110, v151 offset:26896
	ds_write_b16_d16_hi v110, v151 offset:27032
	ds_write_b16 v110, v152 offset:27168
	ds_write_b16_d16_hi v110, v152 offset:27304
	ds_write_b16 v110, v153 offset:27440
	ds_write_b16_d16_hi v110, v153 offset:27576
	s_branch .Lat_stdone_0

.Lat_stdone_0:
	s_andn2_b64 vcc, exec, s[10:11]
	s_cbranch_vccnz .Lat_nomask0_0
	v_add_u32_e32 v126, s23, v119
	v_sub_u32_e32 v126, v116, v126
	v_add_u32_e32 v126, 0x1f00, v126
	v_cmp_gt_i32_e32 vcc, 0, v126
	v_cmp_gt_i32_e64 s[40:41], 1, v126
	v_cmp_gt_i32_e64 s[42:43], 2, v126
	v_cndmask_b32_e32 v32, v32, v221, vcc
	v_cmp_gt_i32_e32 vcc, 3, v126
	v_cndmask_b32_e64 v33, v33, v221, s[40:41]
	v_cmp_gt_i32_e64 s[40:41], 8, v126
	v_cndmask_b32_e64 v34, v34, v221, s[42:43]
	v_cmp_gt_i32_e64 s[42:43], 9, v126
	v_cndmask_b32_e32 v35, v35, v221, vcc
	v_cmp_gt_i32_e32 vcc, 10, v126
	v_cndmask_b32_e64 v36, v36, v221, s[40:41]
	v_cmp_gt_i32_e64 s[40:41], 11, v126
	v_cndmask_b32_e64 v37, v37, v221, s[42:43]
	v_cmp_gt_i32_e64 s[42:43], 16, v126
	v_cndmask_b32_e32 v38, v38, v221, vcc
	v_cmp_gt_i32_e32 vcc, 17, v126
	v_cndmask_b32_e64 v39, v39, v221, s[40:41]
	v_cmp_gt_i32_e64 s[40:41], 18, v126
	v_cndmask_b32_e64 v40, v40, v221, s[42:43]
	v_cmp_gt_i32_e64 s[42:43], 19, v126
	v_cndmask_b32_e32 v41, v41, v221, vcc
	v_cmp_gt_i32_e32 vcc, 24, v126
	v_cndmask_b32_e64 v42, v42, v221, s[40:41]
	v_cmp_gt_i32_e64 s[40:41], 25, v126
	v_cndmask_b32_e64 v43, v43, v221, s[42:43]
	v_cmp_gt_i32_e64 s[42:43], 26, v126
	v_cndmask_b32_e32 v44, v44, v221, vcc
	v_cmp_gt_i32_e32 vcc, 27, v126
	v_cndmask_b32_e64 v45, v45, v221, s[40:41]
	v_cndmask_b32_e64 v46, v46, v221, s[42:43]
	s_nop 0
	v_cndmask_b32_e32 v47, v47, v221, vcc
.Lat_nomask0_0:
	v_exp_f32_e32 v172, v32
	v_exp_f32_e32 v173, v33
	v_exp_f32_e32 v174, v34
	v_exp_f32_e32 v175, v35
	v_mfma_f32_32x32x16_bf16 v[48:63], v[222:225], v[80:83], v[48:63]
	v_exp_f32_e32 v176, v36
	v_exp_f32_e32 v177, v37
	v_exp_f32_e32 v178, v38
	v_exp_f32_e32 v179, v39
	v_mfma_f32_32x32x16_bf16 v[48:63], v[226:229], v[84:87], v[48:63]
	v_exp_f32_e32 v180, v40
	v_exp_f32_e32 v181, v41
	v_exp_f32_e32 v182, v42
	v_exp_f32_e32 v183, v43
	v_mfma_f32_32x32x16_bf16 v[48:63], v[230:233], v[88:91], v[48:63]
	v_exp_f32_e32 v184, v44
	v_exp_f32_e32 v185, v45
	v_exp_f32_e32 v186, v46
	v_exp_f32_e32 v187, v47
	ds_read2_b64 v[198:201], v124 offset0:8 offset1:10
	ds_read2_b64 v[202:205], v124 offset0:12 offset1:14
	ds_read2_b64 v[206:209], v125 offset0:40 offset1:42
	ds_read2_b64 v[222:225], v125 offset0:44 offset1:46
	v_add_f32_e32 v138, v172, v174
	v_add_f32_e32 v139, v173, v175
	v_cvt_pk_bf16_f32 v130, v172, v173
	v_cvt_pk_bf16_f32 v131, v174, v175
	v_add_f32_e32 v138, v138, v176
	v_add_f32_e32 v139, v139, v177
	v_cvt_pk_bf16_f32 v132, v176, v177
	v_add_f32_e32 v138, v138, v178
	v_add_f32_e32 v139, v139, v179
	v_cvt_pk_bf16_f32 v133, v178, v179
	v_add_f32_e32 v138, v138, v180
	v_add_f32_e32 v139, v139, v181
	v_cvt_pk_bf16_f32 v134, v180, v181
	v_add_f32_e32 v138, v138, v182
	v_add_f32_e32 v139, v139, v183
	v_cvt_pk_bf16_f32 v135, v182, v183
	v_add_f32_e32 v138, v138, v184
	v_add_f32_e32 v139, v139, v185
	v_cvt_pk_bf16_f32 v136, v184, v185
	v_add_f32_e32 v138, v138, v186
	v_add_f32_e32 v139, v139, v187
	v_cvt_pk_bf16_f32 v137, v186, v187
	v_add_f32_e32 v138, v138, v139
	v_cmp_lt_f32_e32 vcc, 0x43800000, v138
	s_or_b64 vcc, vcc, s[66:67]
	s_cbranch_vccnz .Lat_slow0_0

; #define LAS __attribute__((address_space(3)))
; __device__ __forceinline__ void attn_unit(LAS unsigned char* lds, const bf16* Q, const bf16* Kp, const bf16* V, bf16* Y, int b, int h, int qb) {
;     ...
;             for (int d0 = 0; d0 < 6; ++d0) p0 = __builtin_amdgcn_mfma_f32_32x32x16_bf16(*(LAS const bf16x8*)(kb + 32 * d0), qr[d0], p0, 0, 0, 0);
; #pragma unroll
;             for (int d0 = 0; d0 < 6; ++d0) p1 = __builtin_amdgcn_mfma_f32_32x32x16_bf16(*(LAS const bf16x8*)(kb + 32 * KPB + 32 * d0), qr[d0], p1, 0, 0, 0);
;     ...
;         if (t + 1 < NT) A_STORE(buf ^ 1);
.Lat_kpre_0:
	s_and_b64 vcc, exec, s[52:53]
	s_cbranch_vccz .Lat_latch_0
	v_add_u32_e32 v110, s46, v117
	ds_read_b128 v[172:175], v110
	ds_read_b128 v[176:179], v110 offset:32
	ds_read_b128 v[180:183], v110 offset:64
	ds_read_b128 v[184:187], v110 offset:96
	ds_read_b128 v[188:191], v110 offset:128
	ds_read_b128 v[192:195], v110 offset:160
	ds_read_b128 v[198:201], v110 offset:6656
	ds_read_b128 v[202:205], v110 offset:6688
	ds_read_b128 v[206:209], v110 offset:6720
	ds_read_b128 v[222:225], v110 offset:6752
	ds_read_b128 v[226:229], v110 offset:6784
	ds_read_b128 v[230:233], v110 offset:6816
	s_branch .Lat_latch_0
.Lat_stage_0:
	s_andn2_b64 vcc, exec, s[6:7]
	s_cbranch_vccnz .Lat_skdone_0
	s_and_b64 vcc, exec, s[50:51]
	s_cbranch_vccz .Lat_w0s_0
	s_waitcnt vmcnt(3)
	s_branch .Lat_w1s_0

.Lat_st2s_0:
	s_or_b64 exec, exec, s[54:55]
	v_add_u32_e32 v110, s49, v115
	ds_write_b16 v110, v150 offset:26624
	ds_write_b16_d16_hi v110, v150 offset:26760
	ds_write_b16 v110, v151 offset:26896
	ds_write_b16_d16_hi v110, v151 offset:27032
	ds_write_b16 v110, v152 offset:27168
	ds_write_b16_d16_hi v110, v152 offset:27304
	ds_write_b16 v110, v153 offset:27440
	ds_write_b16_d16_hi v110, v153 offset:27576

; #define A_LOAD(t) do { kreg0 = *(const u32x4*)(kg + (size_t)((t) * 64 + kv0) * 768 + kc0 * 8); if (tid < 256) kreg1 = *(const u32x4*)(kg + (size_t)((t) * 64 + kv1) * 768 + kc1 * 8); \
;         vreg = *(const u32x4*)(vg + (size_t)(t) * 64 * 512); } while (0)
; __device__ __forceinline__ void attn_unit(LAS unsigned char* lds, const bf16* Q, const bf16* Kp, const bf16* V, bf16* Y, int b, int h, int qb) {
;     ...
;     for (int t = 0; t < NT; ++t) {
;         const int buf = t & 1;
;         if (t + 1 < NT) A_LOAD(t + 1);
;     ...
;         __syncthreads();
.Lat_latch_0:
	s_mov_b32 s24, s44
	s_mov_b32 s25, s45
	s_mov_b32 s44, s46
	s_mov_b32 s45, s47
	s_mov_b32 s46, s48
	s_mov_b32 s47, s49
	s_mov_b32 s48, s24
	s_mov_b32 s49, s25
	s_add_i32 s13, s13, 1
	s_add_i32 s23, s23, 64
	s_mov_b64 s[6:7], 0x10000
	v_lshl_add_u64 v[108:109], v[108:109], 0, s[6:7]
	s_barrier
.Lat_head1:
	s_add_i32 s25, s13, 2
	s_cmp_lt_u32 s25, s12
	s_cselect_b64 s[50:51], -1, 0
	s_cbranch_scc0 .Lat_noload_1
	v_add_u32_e32 v32, s23, v121
	v_add_u32_e32 v32, 0x80, v32
	v_mad_i64_i32 v[32:33], s[10:11], v32, s87, v[66:67]
	global_load_dwordx4 v[142:145], v[32:33], off
	v_mov_b64_e32 v[34:35], v[32:33]
	s_and_saveexec_b64 s[10:11], s[38:39]
	v_add_u32_e32 v36, s23, v120
	v_add_u32_e32 v36, 0x80, v36
	v_mad_i64_i32 v[34:35], s[24:25], v36, s87, v[106:107]
	s_or_b64 exec, exec, s[10:11]
	global_load_dwordx4 v[146:149], v[34:35], off
	global_load_dwordx4 v[150:153], v[108:109], off

.Lat_w1h_1:
	v_add3_u32 v110, s48, v65, v111
	ds_write_b128 v110, v[92:95]
	s_and_saveexec_b64 s[54:55], s[38:39]
	s_cbranch_execz .Lat_st2h_1
	v_add3_u32 v110, s48, v114, v113
	ds_write_b128 v110, v[96:99]
.Lat_st2h_1:
	s_or_b64 exec, exec, s[54:55]
	v_add_u32_e32 v110, s49, v115
	ds_write_b16 v110, v100 offset:26624
	ds_write_b16_d16_hi v110, v100 offset:26760
	ds_write_b16 v110, v101 offset:26896
	ds_write_b16_d16_hi v110, v101 offset:27032
	ds_write_b16 v110, v102 offset:27168
	ds_write_b16_d16_hi v110, v102 offset:27304
	ds_write_b16 v110, v103 offset:27440
	ds_write_b16_d16_hi v110, v103 offset:27576
	s_branch .Lat_stdone_1

.Lat_st2s_1:
	s_or_b64 exec, exec, s[54:55]
	v_add_u32_e32 v110, s49, v115
	ds_write_b16 v110, v100 offset:26624
	ds_write_b16_d16_hi v110, v100 offset:26760
	ds_write_b16 v110, v101 offset:26896
	ds_write_b16_d16_hi v110, v101 offset:27032
	ds_write_b16 v110, v102 offset:27168
	ds_write_b16_d16_hi v110, v102 offset:27304
	ds_write_b16 v110, v103 offset:27440
	ds_write_b16_d16_hi v110, v103 offset:27576

; __device__ __forceinline__ void attn_unit(LAS unsigned char* lds, const bf16* Q, const bf16* Kp, const bf16* V, bf16* Y, int b, int h, int qb) {
;     ...
;         __syncthreads();
;     }
.Lat_latch_1:
	s_mov_b32 s24, s44
	s_mov_b32 s25, s45
	s_mov_b32 s44, s46
	s_mov_b32 s45, s47
	s_mov_b32 s46, s48
	s_mov_b32 s47, s49
	s_mov_b32 s48, s24
	s_mov_b32 s49, s25
	s_add_i32 s13, s13, 1
	s_add_i32 s23, s23, 64
	s_add_i32 s6, s22, s13
	s_cmpk_lg_i32 s6, 0x81
	s_mov_b64 s[6:7], 0x10000
	v_lshl_add_u64 v[108:109], v[108:109], 0, s[6:7]
	s_barrier
	s_cbranch_scc1 .Lat_head
	s_branch .LBB0_3656
.Lat_slow0_0:
	s_nop 7
	v_max3_f32 v127, v32, v33, v34
	v_max3_f32 v128, v35, v36, v37
	v_max3_f32 v127, v127, v38, v39
	v_max3_f32 v128, v128, v40, v41
	v_max3_f32 v127, v127, v42, v43
	v_max3_f32 v128, v128, v44, v45
	v_max3_f32 v127, v127, v46, v47
	v_max_f32_e32 v127, v127, v128
	v_mov_b32_e32 v128, v127
	s_nop 1
	v_permlane32_swap_b32_e32 v127, v128
	v_max_f32_e32 v127, v127, v128
	v_max_f32_e32 v128, 0, v127
	s_nop 0
	v_cndmask_b32_e64 v128, v128, v127, s[66:67]
	s_mov_b64 s[66:67], 0
	v_exp_f32_e64 v129, -v128
	v_add_f32_e32 v122, v122, v128
	v_sub_f32_e32 v32, v32, v128
	v_sub_f32_e32 v33, v33, v128
	v_sub_f32_e32 v34, v34, v128
	v_sub_f32_e32 v35, v35, v128
	v_sub_f32_e32 v36, v36, v128
	v_sub_f32_e32 v37, v37, v128
	v_sub_f32_e32 v38, v38, v128
	v_sub_f32_e32 v39, v39, v128
	v_sub_f32_e32 v40, v40, v128
	v_sub_f32_e32 v41, v41, v128
	v_sub_f32_e32 v42, v42, v128
	v_sub_f32_e32 v43, v43, v128
	v_sub_f32_e32 v44, v44, v128
	v_sub_f32_e32 v45, v45, v128
	v_sub_f32_e32 v46, v46, v128
	v_sub_f32_e32 v47, v47, v128
	v_sub_f32_e32 v48, v48, v128
	v_sub_f32_e32 v49, v49, v128
	v_sub_f32_e32 v50, v50, v128
	v_sub_f32_e32 v51, v51, v128
	v_sub_f32_e32 v52, v52, v128
	v_sub_f32_e32 v53, v53, v128
	v_sub_f32_e32 v54, v54, v128
	v_sub_f32_e32 v55, v55, v128
	v_sub_f32_e32 v56, v56, v128
	v_sub_f32_e32 v57, v57, v128
	v_sub_f32_e32 v58, v58, v128
	v_sub_f32_e32 v59, v59, v128
	v_sub_f32_e32 v60, v60, v128
	v_sub_f32_e32 v61, v61, v128
	v_sub_f32_e32 v62, v62, v128
	v_sub_f32_e32 v63, v63, v128
	v_mul_f32_e32 v0, v0, v129
	v_mul_f32_e32 v1, v1, v129
	v_mul_f32_e32 v2, v2, v129
	v_mul_f32_e32 v3, v3, v129
	v_mul_f32_e32 v4, v4, v129
	v_mul_f32_e32 v5, v5, v129
	v_mul_f32_e32 v6, v6, v129
	v_mul_f32_e32 v7, v7, v129
	v_mul_f32_e32 v8, v8, v129
	v_mul_f32_e32 v9, v9, v129
	v_mul_f32_e32 v10, v10, v129
	v_mul_f32_e32 v11, v11, v129
	v_mul_f32_e32 v12, v12, v129
	v_mul_f32_e32 v13, v13, v129
	v_mul_f32_e32 v14, v14, v129
	v_mul_f32_e32 v15, v15, v129
	v_mul_f32_e32 v16, v16, v129
	v_mul_f32_e32 v17, v17, v129
	v_mul_f32_e32 v18, v18, v129
	v_mul_f32_e32 v19, v19, v129
	v_mul_f32_e32 v20, v20, v129
	v_mul_f32_e32 v21, v21, v129
	v_mul_f32_e32 v22, v22, v129
	v_mul_f32_e32 v23, v23, v129
	v_mul_f32_e32 v24, v24, v129
	v_mul_f32_e32 v25, v25, v129
	v_mul_f32_e32 v26, v26, v129
	v_mul_f32_e32 v27, v27, v129
	v_mul_f32_e32 v28, v28, v129
	v_mul_f32_e32 v29, v29, v129
	v_mul_f32_e32 v30, v30, v129
	v_mul_f32_e32 v31, v31, v129
	v_mul_f32_e32 v123, v123, v129
	v_exp_f32_e32 v172, v32
	v_exp_f32_e32 v173, v33
	v_exp_f32_e32 v174, v34
	v_exp_f32_e32 v175, v35
	v_exp_f32_e32 v176, v36
	v_exp_f32_e32 v177, v37
	v_exp_f32_e32 v178, v38
	v_exp_f32_e32 v179, v39
	v_exp_f32_e32 v180, v40
	v_exp_f32_e32 v181, v41
	v_exp_f32_e32 v182, v42
	v_exp_f32_e32 v183, v43
	v_exp_f32_e32 v184, v44
	v_exp_f32_e32 v185, v45
	v_exp_f32_e32 v186, v46
	v_exp_f32_e32 v187, v47
	v_add_f32_e32 v138, v172, v174
	v_add_f32_e32 v139, v173, v175
	v_cvt_pk_bf16_f32 v130, v172, v173
	v_cvt_pk_bf16_f32 v131, v174, v175
	v_add_f32_e32 v138, v138, v176
	v_add_f32_e32 v139, v139, v177
	v_cvt_pk_bf16_f32 v132, v176, v177
	v_add_f32_e32 v138, v138, v178
	v_add_f32_e32 v139, v139, v179
	v_cvt_pk_bf16_f32 v133, v178, v179
	v_add_f32_e32 v138, v138, v180
	v_add_f32_e32 v139, v139, v181
	v_cvt_pk_bf16_f32 v134, v180, v181
	v_add_f32_e32 v138, v138, v182
	v_add_f32_e32 v139, v139, v183
	v_cvt_pk_bf16_f32 v135, v182, v183
	v_add_f32_e32 v138, v138, v184
	v_add_f32_e32 v139, v139, v185
	v_cvt_pk_bf16_f32 v136, v184, v185
	v_add_f32_e32 v138, v138, v186
	v_add_f32_e32 v139, v139, v187
	v_cvt_pk_bf16_f32 v137, v186, v187
	v_add_f32_e32 v138, v138, v139
	s_branch .Lat_cont0_0
.Lat_slow1_0:
	s_nop 7
	v_max3_f32 v127, v48, v49, v50
	v_max3_f32 v128, v51, v52, v53
	v_max3_f32 v127, v127, v54, v55
	v_max3_f32 v128, v128, v56, v57
	v_max3_f32 v127, v127, v58, v59
	v_max3_f32 v128, v128, v60, v61
	v_max3_f32 v127, v127, v62, v63
	v_max_f32_e32 v127, v127, v128
	v_mov_b32_e32 v128, v127
	s_nop 1
	v_permlane32_swap_b32_e32 v127, v128
	v_max_f32_e32 v127, v127, v128
	v_max_f32_e32 v128, 0, v127
	v_exp_f32_e64 v129, -v128
	v_add_f32_e32 v122, v122, v128
	v_sub_f32_e32 v48, v48, v128
	v_sub_f32_e32 v49, v49, v128
	v_sub_f32_e32 v50, v50, v128
	v_sub_f32_e32 v51, v51, v128
	v_sub_f32_e32 v52, v52, v128
	v_sub_f32_e32 v53, v53, v128
	v_sub_f32_e32 v54, v54, v128
	v_sub_f32_e32 v55, v55, v128
	v_sub_f32_e32 v56, v56, v128
	v_sub_f32_e32 v57, v57, v128
	v_sub_f32_e32 v58, v58, v128
	v_sub_f32_e32 v59, v59, v128
	v_sub_f32_e32 v60, v60, v128
	v_sub_f32_e32 v61, v61, v128
	v_sub_f32_e32 v62, v62, v128
	v_sub_f32_e32 v63, v63, v128
	v_mul_f32_e32 v0, v0, v129
	v_mul_f32_e32 v1, v1, v129
	v_mul_f32_e32 v2, v2, v129
	v_mul_f32_e32 v3, v3, v129
	v_mul_f32_e32 v4, v4, v129
	v_mul_f32_e32 v5, v5, v129
	v_mul_f32_e32 v6, v6, v129
	v_mul_f32_e32 v7, v7, v129
	v_mul_f32_e32 v8, v8, v129
	v_mul_f32_e32 v9, v9, v129
	v_mul_f32_e32 v10, v10, v129
	v_mul_f32_e32 v11, v11, v129
	v_mul_f32_e32 v12, v12, v129
	v_mul_f32_e32 v13, v13, v129
	v_mul_f32_e32 v14, v14, v129
	v_mul_f32_e32 v15, v15, v129
	v_mul_f32_e32 v16, v16, v129
	v_mul_f32_e32 v17, v17, v129
	v_mul_f32_e32 v18, v18, v129
	v_mul_f32_e32 v19, v19, v129
	v_mul_f32_e32 v20, v20, v129
	v_mul_f32_e32 v21, v21, v129
	v_mul_f32_e32 v22, v22, v129
	v_mul_f32_e32 v23, v23, v129
	v_mul_f32_e32 v24, v24, v129
	v_mul_f32_e32 v25, v25, v129
	v_mul_f32_e32 v26, v26, v129
	v_mul_f32_e32 v27, v27, v129
	v_mul_f32_e32 v28, v28, v129
	v_mul_f32_e32 v29, v29, v129
	v_mul_f32_e32 v30, v30, v129
	v_mul_f32_e32 v31, v31, v129
	v_mul_f32_e32 v123, v123, v129
	v_exp_f32_e32 v188, v48
	v_exp_f32_e32 v189, v49
	v_exp_f32_e32 v190, v50
	v_exp_f32_e32 v191, v51
	v_exp_f32_e32 v192, v52
	v_exp_f32_e32 v193, v53
	v_exp_f32_e32 v194, v54
	v_exp_f32_e32 v195, v55
	v_exp_f32_e32 v216, v56
	v_exp_f32_e32 v217, v57
	v_exp_f32_e32 v218, v58
	v_exp_f32_e32 v219, v59
	v_exp_f32_e32 v250, v60
	v_exp_f32_e32 v251, v61
	v_exp_f32_e32 v140, v62
	v_exp_f32_e32 v141, v63
	v_add_f32_e32 v138, v188, v190
	v_add_f32_e32 v139, v189, v191
	v_cvt_pk_bf16_f32 v130, v188, v189
	v_cvt_pk_bf16_f32 v131, v190, v191
	v_add_f32_e32 v138, v138, v192
	v_add_f32_e32 v139, v139, v193
	v_cvt_pk_bf16_f32 v132, v192, v193
	v_add_f32_e32 v138, v138, v194
	v_add_f32_e32 v139, v139, v195
	v_cvt_pk_bf16_f32 v133, v194, v195
	v_add_f32_e32 v138, v138, v216
	v_add_f32_e32 v139, v139, v217
	v_cvt_pk_bf16_f32 v134, v216, v217
	v_add_f32_e32 v138, v138, v218
	v_add_f32_e32 v139, v139, v219
	v_cvt_pk_bf16_f32 v135, v218, v219
	v_add_f32_e32 v138, v138, v250
	v_add_f32_e32 v139, v139, v251
	v_cvt_pk_bf16_f32 v136, v250, v251
	v_add_f32_e32 v138, v138, v140
	v_add_f32_e32 v139, v139, v141
	v_cvt_pk_bf16_f32 v137, v140, v141
	v_add_f32_e32 v138, v138, v139
	s_branch .Lat_cont1_0
